# 4-phase k-loop also for the compress/gate GEMM units (with a store drain before the k-loop)
# speedup vs baseline: 1.0021x; 1.0021x over previous
.LBB0_891:
	s_add_u32 s16, s16, 0x80080
	s_addc_u32 s17, s17, 0
	s_add_u32 s9, s18, 0x100
	v_mov_b32_e32 v0, 0
	s_addc_u32 s11, s19, 0
	s_mov_b32 s15, -2
	v_mov_b32_e32 v1, v0
	v_mov_b32_e32 v2, v0
	v_mov_b32_e32 v3, v0
	v_mov_b32_e32 v4, v0
	v_mov_b32_e32 v5, v0
	v_mov_b32_e32 v6, v0
	v_mov_b32_e32 v7, v0
	v_mov_b32_e32 v8, v0
	v_mov_b32_e32 v9, v0
	v_mov_b32_e32 v10, v0
	v_mov_b32_e32 v11, v0
	v_mov_b32_e32 v12, v0
	v_mov_b32_e32 v13, v0
	v_mov_b32_e32 v14, v0
	v_mov_b32_e32 v15, v0
	v_mov_b32_e32 v20, v0
	v_mov_b32_e32 v21, v0
	v_mov_b32_e32 v22, v0
	v_mov_b32_e32 v23, v0
	v_mov_b32_e32 v28, v0
	v_mov_b32_e32 v29, v0
	v_mov_b32_e32 v30, v0
	v_mov_b32_e32 v31, v0
	v_mov_b32_e32 v38, v0
	v_mov_b32_e32 v39, v0
	v_mov_b32_e32 v40, v0
	v_mov_b32_e32 v41, v0
	v_mov_b32_e32 v46, v0
	v_mov_b32_e32 v47, v0
	v_mov_b32_e32 v48, v0
	v_mov_b32_e32 v49, v0
	v_mov_b32_e32 v16, v0
	v_mov_b32_e32 v17, v0
	v_mov_b32_e32 v18, v0
	v_mov_b32_e32 v19, v0
	v_mov_b32_e32 v24, v0
	v_mov_b32_e32 v25, v0
	v_mov_b32_e32 v26, v0
	v_mov_b32_e32 v27, v0
	v_mov_b32_e32 v34, v0
	v_mov_b32_e32 v35, v0
	v_mov_b32_e32 v36, v0
	v_mov_b32_e32 v37, v0
	v_mov_b32_e32 v42, v0
	v_mov_b32_e32 v43, v0
	v_mov_b32_e32 v44, v0
	v_mov_b32_e32 v45, v0
	v_mov_b32_e32 v50, v0
	v_mov_b32_e32 v51, v0
	v_mov_b32_e32 v52, v0
	v_mov_b32_e32 v53, v0
	v_mov_b32_e32 v54, v0
	v_mov_b32_e32 v55, v0
	v_mov_b32_e32 v56, v0
	v_mov_b32_e32 v57, v0
	v_mov_b32_e32 v58, v0
	v_mov_b32_e32 v59, v0
	v_mov_b32_e32 v60, v0
	v_mov_b32_e32 v61, v0
	v_mov_b32_e32 v62, v0
	v_mov_b32_e32 v63, v0
	v_mov_b32_e32 v64, v0
	v_mov_b32_e32 v65, v0
	v_mov_b32_e32 v66, v0
	v_mov_b32_e32 v67, v0
	v_mov_b32_e32 v68, v0
	v_mov_b32_e32 v69, v0
	v_mov_b32_e32 v70, v0
	v_mov_b32_e32 v71, v0
	v_mov_b32_e32 v72, v0
	v_mov_b32_e32 v73, v0
	v_mov_b32_e32 v74, v0
	v_mov_b32_e32 v75, v0
	v_mov_b32_e32 v76, v0
	v_mov_b32_e32 v77, v0
	v_mov_b32_e32 v78, v0
	v_mov_b32_e32 v79, v0
	v_mov_b32_e32 v80, v0
	v_mov_b32_e32 v81, v0
	v_mov_b32_e32 v86, v0
	v_mov_b32_e32 v87, v0
	v_mov_b32_e32 v88, v0
	v_mov_b32_e32 v89, v0
	v_mov_b32_e32 v94, v0
	v_mov_b32_e32 v95, v0
	v_mov_b32_e32 v96, v0
	v_mov_b32_e32 v97, v0
	v_mov_b32_e32 v102, v0
	v_mov_b32_e32 v103, v0
	v_mov_b32_e32 v104, v0
	v_mov_b32_e32 v105, v0
	v_mov_b32_e32 v110, v0
	v_mov_b32_e32 v111, v0
	v_mov_b32_e32 v112, v0
	v_mov_b32_e32 v113, v0
	v_mov_b32_e32 v82, v0
	v_mov_b32_e32 v83, v0
	v_mov_b32_e32 v84, v0
	v_mov_b32_e32 v85, v0
	v_mov_b32_e32 v90, v0
	v_mov_b32_e32 v91, v0
	v_mov_b32_e32 v92, v0
	v_mov_b32_e32 v93, v0
	v_mov_b32_e32 v98, v0
	v_mov_b32_e32 v99, v0
	v_mov_b32_e32 v100, v0
	v_mov_b32_e32 v101, v0
	v_mov_b32_e32 v106, v0
	v_mov_b32_e32 v107, v0
	v_mov_b32_e32 v108, v0
	v_mov_b32_e32 v109, v0
	v_mov_b32_e32 v114, v0
	v_mov_b32_e32 v115, v0
	v_mov_b32_e32 v116, v0
	v_mov_b32_e32 v117, v0
	v_mov_b32_e32 v118, v0
	v_mov_b32_e32 v119, v0
	v_mov_b32_e32 v120, v0
	v_mov_b32_e32 v121, v0
	v_mov_b32_e32 v122, v0
	v_mov_b32_e32 v123, v0
	v_mov_b32_e32 v124, v0
	v_mov_b32_e32 v125, v0
	v_mov_b32_e32 v126, v0
	v_mov_b32_e32 v127, v0
	v_mov_b32_e32 v128, v0
	v_mov_b32_e32 v129, v0
	s_waitcnt vmcnt(0)
.LBB0_892:
	s_add_u32 s18, s16, 0xfff80080
	s_addc_u32 s19, s17, -1
	s_add_i32 s22, 0, 0x10000
	v_add_u32_e32 v32, s22, v150
	ds_read_b128 v[130:133], v32
	ds_read_b128 v[152:155], v32 offset:1024
	ds_read_b128 v[156:159], v32 offset:2048
	ds_read_b128 v[160:163], v32 offset:3072
	s_cmp_eq_u32 s15, 28
	s_cselect_b32 s21, s5, s19
	s_cselect_b32 s20, s4, s18
	s_cselect_b32 s19, s13, s11
	s_cselect_b32 s18, s12, s9
	s_add_i32 s40, 0, 0x14000
	v_add_u32_e32 v32, s40, v150
	ds_read_b128 v[200:203], v32
	ds_read_b128 v[204:207], v32 offset:1024
	ds_read_b128 v[208:211], v32 offset:2048
	ds_read_b128 v[212:215], v32 offset:3072
	s_add_i32 m0, s30, 0xc000
	s_nop 0
	global_load_lds_dwordx4 v144, s[16:17]
	ds_read_b128 v[164:167], v151
	ds_read_b128 v[168:171], v151 offset:1024
	ds_read_b128 v[172:175], v151 offset:2048
	ds_read_b128 v[180:183], v151 offset:3072
	ds_read_b128 v[184:187], v151 offset:4096
	ds_read_b128 v[188:191], v151 offset:5120
	ds_read_b128 v[192:195], v151 offset:6144
	ds_read_b128 v[196:199], v151 offset:7168
	s_add_i32 m0, s30, 0xe000
	s_nop 0
	global_load_lds_dwordx4 v146, s[16:17]
	s_waitcnt lgkmcnt(0)
	s_barrier
	s_setprio 1
	v_mfma_f32_16x16x32_bf16 v[126:129], v[130:133], v[164:167], v[126:129]
	v_mfma_f32_16x16x32_bf16 v[122:125], v[156:159], v[164:167], v[122:125]
	v_mfma_f32_16x16x32_bf16 v[118:121], v[130:133], v[172:175], v[118:121]
	v_mfma_f32_16x16x32_bf16 v[114:117], v[156:159], v[172:175], v[114:117]
	v_mfma_f32_16x16x32_bf16 v[106:109], v[130:133], v[184:187], v[106:109]
	v_mfma_f32_16x16x32_bf16 v[98:101], v[156:159], v[184:187], v[98:101]
	v_mfma_f32_16x16x32_bf16 v[90:93], v[130:133], v[192:195], v[90:93]
	v_mfma_f32_16x16x32_bf16 v[82:85], v[156:159], v[192:195], v[82:85]
	v_mfma_f32_16x16x32_bf16 v[126:129], v[152:155], v[168:171], v[126:129]
	v_mfma_f32_16x16x32_bf16 v[122:125], v[160:163], v[168:171], v[122:125]
	v_mfma_f32_16x16x32_bf16 v[118:121], v[152:155], v[180:183], v[118:121]
	v_mfma_f32_16x16x32_bf16 v[114:117], v[160:163], v[180:183], v[114:117]
	v_mfma_f32_16x16x32_bf16 v[106:109], v[152:155], v[188:191], v[106:109]
	v_mfma_f32_16x16x32_bf16 v[98:101], v[160:163], v[188:191], v[98:101]
	v_mfma_f32_16x16x32_bf16 v[90:93], v[152:155], v[196:199], v[90:93]
	v_mfma_f32_16x16x32_bf16 v[82:85], v[160:163], v[196:199], v[82:85]
	s_cmp_eq_u32 s14, 2
	s_cbranch_scc1 .Ll3a_skip0
	v_mfma_f32_16x16x32_bf16 v[110:113], v[200:203], v[164:167], v[110:113]
	v_mfma_f32_16x16x32_bf16 v[102:105], v[208:211], v[164:167], v[102:105]
	v_mfma_f32_16x16x32_bf16 v[94:97], v[200:203], v[172:175], v[94:97]
	v_mfma_f32_16x16x32_bf16 v[86:89], v[208:211], v[172:175], v[86:89]
	v_mfma_f32_16x16x32_bf16 v[78:81], v[200:203], v[184:187], v[78:81]
	v_mfma_f32_16x16x32_bf16 v[74:77], v[208:211], v[184:187], v[74:77]
	v_mfma_f32_16x16x32_bf16 v[70:73], v[200:203], v[192:195], v[70:73]
	v_mfma_f32_16x16x32_bf16 v[66:69], v[208:211], v[192:195], v[66:69]
	v_mfma_f32_16x16x32_bf16 v[110:113], v[204:207], v[168:171], v[110:113]
	v_mfma_f32_16x16x32_bf16 v[102:105], v[212:215], v[168:171], v[102:105]
	v_mfma_f32_16x16x32_bf16 v[94:97], v[204:207], v[180:183], v[94:97]
	v_mfma_f32_16x16x32_bf16 v[86:89], v[212:215], v[180:183], v[86:89]
	v_mfma_f32_16x16x32_bf16 v[78:81], v[204:207], v[188:191], v[78:81]
	v_mfma_f32_16x16x32_bf16 v[74:77], v[212:215], v[188:191], v[74:77]
	v_mfma_f32_16x16x32_bf16 v[70:73], v[204:207], v[196:199], v[70:73]
	v_mfma_f32_16x16x32_bf16 v[66:69], v[212:215], v[196:199], v[66:69]
.Ll3a_skip0:
	s_setprio 0
	s_barrier
	ds_read_b128 v[164:167], v151 offset:16384
	ds_read_b128 v[168:171], v151 offset:17408
	ds_read_b128 v[172:175], v151 offset:18432
	ds_read_b128 v[180:183], v151 offset:19456
	ds_read_b128 v[184:187], v151 offset:20480
	ds_read_b128 v[188:191], v151 offset:21504
	ds_read_b128 v[192:195], v151 offset:22528
	ds_read_b128 v[196:199], v151 offset:23552
	s_add_i32 m0, s29, 0x10000
	s_nop 0
	global_load_lds_dwordx4 v138, s[18:19]
	s_add_i32 m0, s29, 0x12000
	s_nop 0
	global_load_lds_dwordx4 v134, s[18:19]
	s_mov_b32 m0, s30
	s_nop 0
	global_load_lds_dwordx4 v140, s[20:21]
	s_mov_b32 m0, s31
	s_nop 0
	global_load_lds_dwordx4 v136, s[20:21]
	s_add_u32 s22, s18, 0x80000
	s_addc_u32 s23, s19, 0
	s_add_i32 m0, s29, 0x14000
	s_nop 0
	global_load_lds_dwordx4 v138, s[22:23]
	s_add_i32 m0, s29, 0x16000
	s_nop 0
	global_load_lds_dwordx4 v134, s[22:23]
	s_waitcnt vmcnt(6)
	s_waitcnt lgkmcnt(0)
	s_barrier
	s_setprio 1
	v_mfma_f32_16x16x32_bf16 v[62:65], v[130:133], v[164:167], v[62:65]
	v_mfma_f32_16x16x32_bf16 v[58:61], v[156:159], v[164:167], v[58:61]
	v_mfma_f32_16x16x32_bf16 v[54:57], v[130:133], v[172:175], v[54:57]
	v_mfma_f32_16x16x32_bf16 v[50:53], v[156:159], v[172:175], v[50:53]
	v_mfma_f32_16x16x32_bf16 v[42:45], v[130:133], v[184:187], v[42:45]
	v_mfma_f32_16x16x32_bf16 v[34:37], v[156:159], v[184:187], v[34:37]
	v_mfma_f32_16x16x32_bf16 v[24:27], v[130:133], v[192:195], v[24:27]
	v_mfma_f32_16x16x32_bf16 v[16:19], v[156:159], v[192:195], v[16:19]
	v_mfma_f32_16x16x32_bf16 v[62:65], v[152:155], v[168:171], v[62:65]
	v_mfma_f32_16x16x32_bf16 v[58:61], v[160:163], v[168:171], v[58:61]
	v_mfma_f32_16x16x32_bf16 v[54:57], v[152:155], v[180:183], v[54:57]
	v_mfma_f32_16x16x32_bf16 v[50:53], v[160:163], v[180:183], v[50:53]
	v_mfma_f32_16x16x32_bf16 v[42:45], v[152:155], v[188:191], v[42:45]
	v_mfma_f32_16x16x32_bf16 v[34:37], v[160:163], v[188:191], v[34:37]
	v_mfma_f32_16x16x32_bf16 v[24:27], v[152:155], v[196:199], v[24:27]
	v_mfma_f32_16x16x32_bf16 v[16:19], v[160:163], v[196:199], v[16:19]
	s_cmp_eq_u32 s14, 2
	s_cbranch_scc1 .Ll3a_skip1
	v_mfma_f32_16x16x32_bf16 v[46:49], v[200:203], v[164:167], v[46:49]
	v_mfma_f32_16x16x32_bf16 v[38:41], v[208:211], v[164:167], v[38:41]
	v_mfma_f32_16x16x32_bf16 v[28:31], v[200:203], v[172:175], v[28:31]
	v_mfma_f32_16x16x32_bf16 v[20:23], v[208:211], v[172:175], v[20:23]
	v_mfma_f32_16x16x32_bf16 v[12:15], v[200:203], v[184:187], v[12:15]
	v_mfma_f32_16x16x32_bf16 v[8:11], v[208:211], v[184:187], v[8:11]
	v_mfma_f32_16x16x32_bf16 v[4:7], v[200:203], v[192:195], v[4:7]
	v_mfma_f32_16x16x32_bf16 v[0:3], v[208:211], v[192:195], v[0:3]
	v_mfma_f32_16x16x32_bf16 v[46:49], v[204:207], v[168:171], v[46:49]
	v_mfma_f32_16x16x32_bf16 v[38:41], v[212:215], v[168:171], v[38:41]
	v_mfma_f32_16x16x32_bf16 v[28:31], v[204:207], v[180:183], v[28:31]
	v_mfma_f32_16x16x32_bf16 v[20:23], v[212:215], v[180:183], v[20:23]
	v_mfma_f32_16x16x32_bf16 v[12:15], v[204:207], v[188:191], v[12:15]
	v_mfma_f32_16x16x32_bf16 v[8:11], v[212:215], v[188:191], v[8:11]
	v_mfma_f32_16x16x32_bf16 v[4:7], v[204:207], v[196:199], v[4:7]
	v_mfma_f32_16x16x32_bf16 v[0:3], v[212:215], v[196:199], v[0:3]
.Ll3a_skip1:
	s_setprio 0
	s_add_i32 s22, 0, 0x18000
	v_add_u32_e32 v32, s22, v150
	s_barrier
	ds_read_b128 v[130:133], v32
	ds_read_b128 v[152:155], v32 offset:1024
	ds_read_b128 v[156:159], v32 offset:2048
	ds_read_b128 v[160:163], v32 offset:3072
	s_add_u32 s20, s20, 0x80000
	s_addc_u32 s21, s21, 0
	s_add_i32 s22, 0, 0x1c000
	v_add_u32_e32 v32, s22, v150
	ds_read_b128 v[200:203], v32
	ds_read_b128 v[204:207], v32 offset:1024
	ds_read_b128 v[208:211], v32 offset:2048
	ds_read_b128 v[212:215], v32 offset:3072
	s_mov_b32 m0, s34
	s_nop 0
	global_load_lds_dwordx4 v140, s[20:21]
	ds_read_b128 v[164:167], v151 offset:32768
	ds_read_b128 v[168:171], v151 offset:33792
	ds_read_b128 v[172:175], v151 offset:34816
	ds_read_b128 v[180:183], v151 offset:35840
	ds_read_b128 v[184:187], v151 offset:36864
	ds_read_b128 v[188:191], v151 offset:37888
	ds_read_b128 v[192:195], v151 offset:38912
	ds_read_b128 v[196:199], v151 offset:39936
	s_mov_b32 m0, s35
	s_nop 0
	global_load_lds_dwordx4 v136, s[20:21]
	s_waitcnt lgkmcnt(0)
	s_barrier
	s_setprio 1
	v_mfma_f32_16x16x32_bf16 v[126:129], v[130:133], v[164:167], v[126:129]
	v_mfma_f32_16x16x32_bf16 v[122:125], v[156:159], v[164:167], v[122:125]
	v_mfma_f32_16x16x32_bf16 v[118:121], v[130:133], v[172:175], v[118:121]
	v_mfma_f32_16x16x32_bf16 v[114:117], v[156:159], v[172:175], v[114:117]
	v_mfma_f32_16x16x32_bf16 v[106:109], v[130:133], v[184:187], v[106:109]
	v_mfma_f32_16x16x32_bf16 v[98:101], v[156:159], v[184:187], v[98:101]
	v_mfma_f32_16x16x32_bf16 v[90:93], v[130:133], v[192:195], v[90:93]
	v_mfma_f32_16x16x32_bf16 v[82:85], v[156:159], v[192:195], v[82:85]
	v_mfma_f32_16x16x32_bf16 v[126:129], v[152:155], v[168:171], v[126:129]
	v_mfma_f32_16x16x32_bf16 v[122:125], v[160:163], v[168:171], v[122:125]
	v_mfma_f32_16x16x32_bf16 v[118:121], v[152:155], v[180:183], v[118:121]
	v_mfma_f32_16x16x32_bf16 v[114:117], v[160:163], v[180:183], v[114:117]
	v_mfma_f32_16x16x32_bf16 v[106:109], v[152:155], v[188:191], v[106:109]
	v_mfma_f32_16x16x32_bf16 v[98:101], v[160:163], v[188:191], v[98:101]
	v_mfma_f32_16x16x32_bf16 v[90:93], v[152:155], v[196:199], v[90:93]
	v_mfma_f32_16x16x32_bf16 v[82:85], v[160:163], v[196:199], v[82:85]
	s_cmp_eq_u32 s14, 2
	s_cbranch_scc1 .Ll3a_skip2
	v_mfma_f32_16x16x32_bf16 v[110:113], v[200:203], v[164:167], v[110:113]
	v_mfma_f32_16x16x32_bf16 v[102:105], v[208:211], v[164:167], v[102:105]
	v_mfma_f32_16x16x32_bf16 v[94:97], v[200:203], v[172:175], v[94:97]
	v_mfma_f32_16x16x32_bf16 v[86:89], v[208:211], v[172:175], v[86:89]
	v_mfma_f32_16x16x32_bf16 v[78:81], v[200:203], v[184:187], v[78:81]
	v_mfma_f32_16x16x32_bf16 v[74:77], v[208:211], v[184:187], v[74:77]
	v_mfma_f32_16x16x32_bf16 v[70:73], v[200:203], v[192:195], v[70:73]
	v_mfma_f32_16x16x32_bf16 v[66:69], v[208:211], v[192:195], v[66:69]
	v_mfma_f32_16x16x32_bf16 v[110:113], v[204:207], v[168:171], v[110:113]
	v_mfma_f32_16x16x32_bf16 v[102:105], v[212:215], v[168:171], v[102:105]
	v_mfma_f32_16x16x32_bf16 v[94:97], v[204:207], v[180:183], v[94:97]
	v_mfma_f32_16x16x32_bf16 v[86:89], v[212:215], v[180:183], v[86:89]
	v_mfma_f32_16x16x32_bf16 v[78:81], v[204:207], v[188:191], v[78:81]
	v_mfma_f32_16x16x32_bf16 v[74:77], v[212:215], v[188:191], v[74:77]
	v_mfma_f32_16x16x32_bf16 v[70:73], v[204:207], v[196:199], v[70:73]
	v_mfma_f32_16x16x32_bf16 v[66:69], v[212:215], v[196:199], v[66:69]
.Ll3a_skip2:
	s_setprio 0
	s_barrier
	ds_read_b128 v[164:167], v151 offset:49152
	ds_read_b128 v[168:171], v151 offset:50176
	ds_read_b128 v[172:175], v151 offset:51200
	ds_read_b128 v[180:183], v151 offset:52224
	ds_read_b128 v[184:187], v151 offset:53248
	ds_read_b128 v[188:191], v151 offset:54272
	ds_read_b128 v[192:195], v151 offset:55296
	ds_read_b128 v[196:199], v151 offset:56320
	s_add_u32 s18, s18, 0x80
	s_addc_u32 s19, s19, 0
	s_add_i32 m0, s29, 0x18000
	s_nop 0
	global_load_lds_dwordx4 v138, s[18:19]
	s_add_i32 m0, s29, 0x1a000
	s_nop 0
	global_load_lds_dwordx4 v134, s[18:19]
	s_add_u32 s20, s20, 0xfff80080
	s_addc_u32 s21, s21, -1
	s_mov_b32 m0, s36
	s_nop 0
	global_load_lds_dwordx4 v140, s[20:21]
	s_mov_b32 m0, s37
	s_nop 0
	global_load_lds_dwordx4 v136, s[20:21]
	s_add_u32 s18, s18, 0x80000
	s_addc_u32 s19, s19, 0
	s_add_i32 m0, s29, 0x1c000
	s_nop 0
	global_load_lds_dwordx4 v138, s[18:19]
	s_add_i32 m0, s29, 0x1e000
	s_nop 0
	global_load_lds_dwordx4 v134, s[18:19]
	s_waitcnt vmcnt(6)
	s_waitcnt lgkmcnt(0)
	s_barrier
	s_setprio 1
	v_mfma_f32_16x16x32_bf16 v[62:65], v[130:133], v[164:167], v[62:65]
	v_mfma_f32_16x16x32_bf16 v[58:61], v[156:159], v[164:167], v[58:61]
	v_mfma_f32_16x16x32_bf16 v[54:57], v[130:133], v[172:175], v[54:57]
	v_mfma_f32_16x16x32_bf16 v[50:53], v[156:159], v[172:175], v[50:53]
	v_mfma_f32_16x16x32_bf16 v[42:45], v[130:133], v[184:187], v[42:45]
	v_mfma_f32_16x16x32_bf16 v[34:37], v[156:159], v[184:187], v[34:37]
	v_mfma_f32_16x16x32_bf16 v[24:27], v[130:133], v[192:195], v[24:27]
	v_mfma_f32_16x16x32_bf16 v[16:19], v[156:159], v[192:195], v[16:19]
	v_mfma_f32_16x16x32_bf16 v[62:65], v[152:155], v[168:171], v[62:65]
	v_mfma_f32_16x16x32_bf16 v[58:61], v[160:163], v[168:171], v[58:61]
	v_mfma_f32_16x16x32_bf16 v[54:57], v[152:155], v[180:183], v[54:57]
	v_mfma_f32_16x16x32_bf16 v[50:53], v[160:163], v[180:183], v[50:53]
	v_mfma_f32_16x16x32_bf16 v[42:45], v[152:155], v[188:191], v[42:45]
	v_mfma_f32_16x16x32_bf16 v[34:37], v[160:163], v[188:191], v[34:37]
	v_mfma_f32_16x16x32_bf16 v[24:27], v[152:155], v[196:199], v[24:27]
	v_mfma_f32_16x16x32_bf16 v[16:19], v[160:163], v[196:199], v[16:19]
	s_cmp_eq_u32 s14, 2
	s_cbranch_scc1 .Ll3a_skip3
	v_mfma_f32_16x16x32_bf16 v[46:49], v[200:203], v[164:167], v[46:49]
	v_mfma_f32_16x16x32_bf16 v[38:41], v[208:211], v[164:167], v[38:41]
	v_mfma_f32_16x16x32_bf16 v[28:31], v[200:203], v[172:175], v[28:31]
	v_mfma_f32_16x16x32_bf16 v[20:23], v[208:211], v[172:175], v[20:23]
	v_mfma_f32_16x16x32_bf16 v[12:15], v[200:203], v[184:187], v[12:15]
	v_mfma_f32_16x16x32_bf16 v[8:11], v[208:211], v[184:187], v[8:11]
	v_mfma_f32_16x16x32_bf16 v[4:7], v[200:203], v[192:195], v[4:7]
	v_mfma_f32_16x16x32_bf16 v[0:3], v[208:211], v[192:195], v[0:3]
	v_mfma_f32_16x16x32_bf16 v[46:49], v[204:207], v[168:171], v[46:49]
	v_mfma_f32_16x16x32_bf16 v[38:41], v[212:215], v[168:171], v[38:41]
	v_mfma_f32_16x16x32_bf16 v[28:31], v[204:207], v[180:183], v[28:31]
	v_mfma_f32_16x16x32_bf16 v[20:23], v[212:215], v[180:183], v[20:23]
	v_mfma_f32_16x16x32_bf16 v[12:15], v[204:207], v[188:191], v[12:15]
	v_mfma_f32_16x16x32_bf16 v[8:11], v[212:215], v[188:191], v[8:11]
	v_mfma_f32_16x16x32_bf16 v[4:7], v[204:207], v[196:199], v[4:7]
	v_mfma_f32_16x16x32_bf16 v[0:3], v[212:215], v[196:199], v[0:3]
